# on top of DPP reductions: split 8 v_pk_fma_f32 in the diff-attention loop into scalar v_fma pairs (bit-identical)
# baseline (speedup 1.0000x reference)
; #define SBAR() __builtin_amdgcn_sched_barrier(0)
; #define SLOAD(k0) do { vs0 = *(const bf16x8*)(vp0 + (long)(k0) * ldv); vs1 = *(const bf16x8*)(vp0 + (long)((k0) + 32) * ldv); \
;     ksg[0] = *(const bf16x8*)(kp0 + (long)(k0) * ldk0); \
;     if constexpr (DQK == 192) { ksg[1] = *(const bf16x8*)(kp0 + (long)((k0) + 32) * ldk0); ksg[2] = *(const bf16x8*)(kp2 + (long)(k0) * ldk1); } } while (0)
; DEVI void partialSM(f32x16& p0, f32x16& p1, float& m_reg, float& mn, float& alpha, float scale) {
;   const float C = scale * 1.4426950408889634f;
;   float pmax = p0[0];
; #pragma unroll
;   for (int r = 1; r < 16; ++r) pmax = fmaxf(pmax, p0[r]);
; #pragma unroll
;   for (int r = 0; r < 16; ++r) pmax = fmaxf(pmax, p1[r]);
;   { auto rr = __builtin_amdgcn_permlane32_swap(__float_as_uint(pmax), __float_as_uint(pmax), false, false);
;     pmax = fmaxf(__uint_as_float(rr[0]), __uint_as_float(rr[1])); }
;   if (__builtin_expect(__all(pmax - m_reg <= ATT_THR / scale), 1)) { mn = m_reg; alpha = 1.f; }
;   else { mn = fmaxf(m_reg, pmax); alpha = __builtin_amdgcn_exp2f((m_reg - mn) * C); m_reg = mn; }
;   const float mnC = -mn * C;
; #pragma unroll
;   for (int r = 0; r < 16; ++r) p0[r] = fmaf(p0[r], C, mnC);
; #pragma unroll
;   for (int r = 0; r < 16; ++r) p1[r] = fmaf(p1[r], C, mnC);
; #pragma unroll
;   for (int r = 0; r < 16; ++r) p0[r] = __builtin_amdgcn_exp2f(p0[r]);
; }
; template <int DQK, bool PIPE>
; DEVI void attn_body(const u16* __restrict__ Qb, int ldq, const u16* __restrict__ K0, int ldk0, const u16* __restrict__ K1, int ldk1,
;                     const u16* __restrict__ Vh, int ldv, u16* __restrict__ Ob, int ldo, int seq, float scale, char* lds) {
;     ...
;     for (int j = 1; j + 1 < NT; j += 2) {
;       SBAR(); QKT(pB0, pB1, K_lds + SHM_K);
;       finishSM(pA0, pA1, alA, l_reg, pa0, pa1, pa2, pa3); SBAR();
;       SLOAD((j + 1) * 64); SBAR();
;       pv_d0(o, vb0, pa0, pa1, pa2, pa3); partialSM(pB0, pB1, m_reg, mnB, alB, scale);
;       __syncthreads(); SWAIT(); SWRITE(0);
;       RESC(alB); __syncthreads();
;       SBAR(); QKT(pA0, pA1, K_lds);
;       finishSM(pB0, pB1, alB, l_reg, pa0, pa1, pa2, pa3); SBAR();
;       SLOAD((j + 2) * 64); SBAR();
;       pv_d0(o, vb0 + SHM_V, pa0, pa1, pa2, pa3); partialSM(pA0, pA1, m_reg, mnA, alA, scale);
;       __syncthreads(); SWAIT(); SWRITE(1);
;       RESC(alA); __syncthreads();
.LBB0_477:
	v_cndmask_b32_e64 v148, v130, v148, s[8:9]
	v_mul_f32_e32 v112, 0xbe38aa3b, v148
	v_mov_b32_e32 v113, v112
	v_fmamk_f32 v80, v80, 0x3e38aa3b, v112
	v_fmamk_f32 v81, v81, 0x3e38aa3b, v112
	v_fmamk_f32 v82, v82, 0x3e38aa3b, v112
	v_fmamk_f32 v83, v83, 0x3e38aa3b, v112
	v_fmamk_f32 v84, v84, 0x3e38aa3b, v112
	v_fmamk_f32 v85, v85, 0x3e38aa3b, v112
	v_fmamk_f32 v86, v86, 0x3e38aa3b, v112
	v_fmamk_f32 v87, v87, 0x3e38aa3b, v112
	v_fmamk_f32 v88, v88, 0x3e38aa3b, v112
	v_fmamk_f32 v89, v89, 0x3e38aa3b, v112
	v_fmamk_f32 v90, v90, 0x3e38aa3b, v112
	v_fmamk_f32 v91, v91, 0x3e38aa3b, v112
	v_fmamk_f32 v92, v92, 0x3e38aa3b, v112
	v_fmamk_f32 v93, v93, 0x3e38aa3b, v112
	v_fmamk_f32 v94, v94, 0x3e38aa3b, v112
	v_fmac_f32_e32 v113, 0x3e38aa3b, v95
	v_exp_f32_e32 v157, v80
	v_exp_f32_e32 v159, v81
	v_exp_f32_e32 v161, v82
	v_exp_f32_e32 v163, v83
	v_exp_f32_e32 v165, v84
	v_exp_f32_e32 v167, v85
	v_exp_f32_e32 v168, v86
	v_exp_f32_e32 v170, v87
	v_exp_f32_e32 v155, v88
	v_exp_f32_e32 v156, v89
	v_exp_f32_e32 v158, v90
	v_exp_f32_e32 v160, v91
	v_exp_f32_e32 v162, v92
	v_exp_f32_e32 v164, v93
	v_exp_f32_e32 v166, v94
	v_exp_f32_e32 v169, v113
	v_fma_f32 v133, v65, s20, v112
	v_fma_f32 v132, v64, s20, v112
	v_add_f32_e32 v64, v149, v150
	v_fmac_f32_e32 v64, v147, v137
	v_add_f32_e32 v137, v153, v154
	s_add_i32 s15, s15, 2
	v_fma_f32 v131, v67, s20, v112
	v_fma_f32 v130, v66, s20, v112
	v_fma_f32 v121, v69, s20, v112
	v_fma_f32 v120, v68, s20, v112
	v_fma_f32 v117, v71, s20, v112
	v_fma_f32 v116, v70, s20, v112
	v_fma_f32 v115, v73, s20, v112
	v_fma_f32 v114, v72, s20, v112
	v_fma_f32 v123, v75, s20, v112
	v_fma_f32 v122, v74, s20, v112
	v_fma_f32 v119, v77, s20, v112
	v_fma_f32 v118, v76, s20, v112
	v_fma_f32 v113, v79, s20, v112
	v_fma_f32 v112, v78, s20, v112
	v_fmac_f32_e32 v137, v64, v152
	v_lshl_add_u64 v[126:127], v[126:127], 0, s[22:23]
	s_cmpk_gt_u32 s15, 0x80
	v_lshl_add_u64 v[128:129], v[128:129], 0, s[22:23]
	s_waitcnt lgkmcnt(0)
	s_barrier
	s_cbranch_scc1 .LBB0_479
	v_mov_b32_e32 v147, v151
	s_branch .LBB0_469
